# mix static assignment rebalanced: 8 workgroups per queue take 4 context items each, 8 take 3 spatial units each, 16 take one latent item
# speedup vs baseline: 1.0073x; 1.0073x over previous
.Lmx_small:
	s_sub_u32 s1, s1, 16
	s_lshl_b32 s9, s1, 2
	s_add_u32 s9, s9, 16
	s_add_u32 s9, s9, s0
	s_cmp_gt_u32 s0, 3
	s_cselect_b32 s9, -1, s9
	s_sub_u32 s10, s1, 8
	s_mul_i32 s10, s10, 3
	s_add_u32 s10, s10, 48
	s_add_u32 s10, s10, s0
	s_cmp_gt_u32 s0, 2
	s_cselect_b32 s10, -1, s10
	s_cmp_lt_u32 s1, 8
	s_cselect_b32 s9, s9, s10
